# no L2 writeback at barriers after merge/W_out/FF1 (same-XCD consumers, placement checked at run time); attention: prio raise waves 0-3, persistent threshold
# speedup vs baseline: 1.0057x; 1.0057x over previous
_Z10fwd_kernel6Params:
	s_load_dwordx4 s[12:15], s[0:1], 0xb0
	v_and_b32_e32 v1, 0x3ff, v0
	s_mov_b32 s92, s2
	s_mov_b64 s[90:91], s[0:1]
	v_readfirstlane_b32 s5, v1
	v_cmp_gt_u32_e32 vcc, 2, v1
	s_and_saveexec_b64 s[0:1], vcc
	v_lshl_add_u32 v2, v1, 2, 0
	v_add_u32_e32 v2, 0x24000, v2
	v_mov_b32_e32 v3, 0
	ds_write_b32 v2, v3
	s_or_b64 exec, exec, s[0:1]
	s_waitcnt lgkmcnt(0)
	s_barrier
	s_getreg_b32 s0, hwreg(HW_REG_XCC_ID, 0, 4)
	s_and_b32 s4, s0, 15
	v_cmp_eq_u32_e64 s[86:87], 0, v1
	s_and_saveexec_b64 s[0:1], s[86:87]
	s_cbranch_execz .LBB0_5
	s_mov_b64 s[2:3], exec
	v_mbcnt_lo_u32_b32 v2, s2, 0
	v_mbcnt_hi_u32_b32 v2, s3, v2
	v_cmp_eq_u32_e32 vcc, 0, v2
	s_and_b64 s[6:7], exec, vcc
	s_mov_b64 exec, s[6:7]
	s_cbranch_execz .LBB0_5
	s_lshl_b32 s6, s4, 8
	s_bcnt1_i32_b64 s2, s[2:3]
	v_mov_b32_e32 v2, s6
	v_mov_b32_e32 v3, s2
	global_atomic_add v2, v3, s[12:13] offset:1024
	s_and_b32 s6, s92, 7
	s_lshl_b32 s6, s6, 2
	s_add_i32 s6, s6, 0x3800
	s_nop 1
	v_mov_b32_e32 v2, s6
	s_lshl_b32 s6, 1, s4
	v_mov_b32_e32 v3, s6
	s_nop 0
	global_atomic_or v2, v3, s[12:13]

.LBB0_11:
	s_cmp_eq_u32 s14, 2
	s_cbranch_scc0 .Lpl_skip
	v_mov_b32_e32 v0, 0x3800
	global_load_dwordx4 v[4:7], v0, s[12:13] sc1
	global_load_dwordx4 v[8:11], v0, s[12:13] offset:16 sc1
	s_mov_b32 s99, 1
	s_waitcnt vmcnt(0)
	v_readfirstlane_b32 s98, v4
	s_bcnt1_i32_b32 s98, s98
	s_cmp_eq_u32 s98, 1
	s_cselect_b32 s99, s99, 0
	v_readfirstlane_b32 s98, v5
	s_bcnt1_i32_b32 s98, s98
	s_cmp_eq_u32 s98, 1
	s_cselect_b32 s99, s99, 0
	v_readfirstlane_b32 s98, v6
	s_bcnt1_i32_b32 s98, s98
	s_cmp_eq_u32 s98, 1
	s_cselect_b32 s99, s99, 0
	v_readfirstlane_b32 s98, v7
	s_bcnt1_i32_b32 s98, s98
	s_cmp_eq_u32 s98, 1
	s_cselect_b32 s99, s99, 0
	v_readfirstlane_b32 s98, v8
	s_bcnt1_i32_b32 s98, s98
	s_cmp_eq_u32 s98, 1
	s_cselect_b32 s99, s99, 0
	v_readfirstlane_b32 s98, v9
	s_bcnt1_i32_b32 s98, s98
	s_cmp_eq_u32 s98, 1
	s_cselect_b32 s99, s99, 0
	v_readfirstlane_b32 s98, v10
	s_bcnt1_i32_b32 s98, s98
	s_cmp_eq_u32 s98, 1
	s_cselect_b32 s99, s99, 0
	v_readfirstlane_b32 s98, v11
	s_bcnt1_i32_b32 s98, s98
	s_cmp_eq_u32 s98, 1
	s_cselect_b32 s99, s99, 0
	v_writelane_b32 v255, s99, 59

.Lam_entry:
	v_and_b32_e32 v152, 31, v203
	v_lshlrev_b32_e32 v152, 8, v152
	v_lshrrev_b32_e32 v153, 5, v203
	v_and_b32_e32 v48, 15, v203
	v_xor_b32_e32 v48, v48, v153
	v_xor_b32_e32 v242, 0, v48
	v_lshl_add_u32 v242, v242, 4, v152
	v_xor_b32_e32 v243, 2, v48
	v_lshl_add_u32 v243, v243, 4, v152
	v_xor_b32_e32 v244, 4, v48
	v_lshl_add_u32 v244, v244, 4, v152
	v_xor_b32_e32 v245, 6, v48
	v_lshl_add_u32 v245, v245, 4, v152
	v_xor_b32_e32 v246, 8, v48
	v_lshl_add_u32 v246, v246, 4, v152
	v_xor_b32_e32 v247, 10, v48
	v_lshl_add_u32 v247, v247, 4, v152
	v_xor_b32_e32 v248, 12, v48
	v_lshl_add_u32 v248, v248, 4, v152
	v_xor_b32_e32 v249, 14, v48
	v_lshl_add_u32 v249, v249, 4, v152
	v_mov_b32_e32 v94, v242
	v_mov_b32_e32 v95, v243
	v_mov_b32_e32 v97, v244
	v_mov_b32_e32 v147, v245
	v_mov_b32_e32 v200, v246
	v_mov_b32_e32 v201, v247
	s_cmp_ge_u32 s48, 4
	s_cbranch_scc1 .Lam_noprio
	s_setprio 1
.Lam_noprio:
	v_add_f32_e32 v252, 0x41000000, v217
	s_mov_b32 s81, s80
	s_lshl_b32 s82, s48, 11
	s_lshl_b32 s83, s48, 10
	s_mov_b64 s[84:85], s[20:21]
	s_mov_b64 s[88:89], s[18:19]
	s_mov_b64 s[86:87], s[38:39]
	s_mov_b64 s[90:91], s[44:45]
	s_mov_b32 s92, 0
	ds_read_b128 v[218:221], v94 offset:8192
	ds_read_b128 v[222:225], v95 offset:8192
	ds_read_b128 v[226:229], v97 offset:8192
	ds_read_b128 v[230:233], v147 offset:8192
	ds_read_b128 v[234:237], v200 offset:8192
	ds_read_b128 v[238:241], v201 offset:8192
.Lam_loop:
	s_waitcnt vmcnt(3)
	s_barrier
	s_add_u32 m0, s82, 0x18000
	v_lshl_add_u64 v[152:153], v[142:143], 0, s[84:85]
	global_load_lds_dwordx4 v[152:153], off
	s_add_u32 m0, s82, 0x18400
	v_lshl_add_u64 v[152:153], v[144:145], 0, s[84:85]
	global_load_lds_dwordx4 v[152:153], off
	s_add_u32 m0, s83, 0x1c000
	v_lshl_add_u64 v[152:153], v[140:141], 0, s[86:87]
	global_load_lds_dwordx4 v[152:153], off
	s_add_u32 m0, s82, 0x1e000
	v_lshl_add_u64 v[152:153], v[142:143], 0, s[88:89]
	global_load_lds_dwordx4 v[152:153], off
	s_add_u32 m0, s82, 0x1e400
	v_lshl_add_u64 v[152:153], v[144:145], 0, s[88:89]
	global_load_lds_dwordx4 v[152:153], off
	s_add_u32 m0, s83, 0x22000
	v_lshl_add_u64 v[152:153], v[140:141], 0, s[90:91]
	global_load_lds_dwordx4 v[152:153], off
	s_add_u32 s84, s84, 0x30000
	s_addc_u32 s85, s85, 0
	s_add_u32 s88, s88, 0x30000
	s_addc_u32 s89, s89, 0
	s_add_u32 s86, s86, 0x100
	s_addc_u32 s87, s87, 0
	s_add_u32 s90, s90, 0x100
	s_addc_u32 s91, s91, 0
	s_cmp_eq_u32 s92, 0
	s_cselect_b32 s93, 0, 0xfffe8000
	s_mov_b32 s92, 1
	v_add_u32_e32 v242, s93, v242
	v_add_u32_e32 v243, s93, v243
	v_add_u32_e32 v244, s93, v244
	v_add_u32_e32 v245, s93, v245
	v_add_u32_e32 v246, s93, v246
	v_add_u32_e32 v247, s93, v247
	v_add_u32_e32 v248, s93, v248
	v_add_u32_e32 v249, s93, v249
	ds_read_b128 v[90:93], v243 offset:16384
	ds_read_b128 v[148:151], v247 offset:16384
	s_waitcnt lgkmcnt(7)
	v_mfma_f32_32x32x16_bf16 v[48:63], v[218:221], v[66:69], 0
	ds_read_b128 v[218:221], v94 offset:24576
	v_max3_f32 v152, v32, v33, v34
	v_max3_f32 v153, v35, v36, v37
	v_max3_f32 v152, v152, v38, v39
	v_max3_f32 v153, v153, v40, v41
	v_max3_f32 v152, v152, v42, v43
	v_max3_f32 v153, v153, v44, v45
	s_waitcnt lgkmcnt(7)
	v_mfma_f32_32x32x16_bf16 v[48:63], v[222:225], v[70:73], v[48:63]
	ds_read_b128 v[222:225], v95 offset:24576
	v_max3_f32 v152, v152, v46, v47
	v_max_f32_e32 v152, v152, v153
	v_mov_b32_e32 v153, v152
	s_nop 1
	v_permlane32_swap_b32_e32 v153, v152
	v_max_f32_e32 v152, v152, v153
	v_cmp_lt_f32_e32 vcc, v252, v152
	s_cbranch_vccnz .Lam_c0u0_rare
.Lam_c0u0_back:
	v_sub_f32_e32 v40, v40, v217
	s_waitcnt lgkmcnt(7)
	v_mfma_f32_32x32x16_bf16 v[48:63], v[226:229], v[74:77], v[48:63]
	ds_read_b128 v[226:229], v97 offset:24576
	v_sub_f32_e32 v41, v41, v217
	v_sub_f32_e32 v42, v42, v217
	v_sub_f32_e32 v43, v43, v217
	v_exp_f32_e32 v40, v40
	v_exp_f32_e32 v41, v41
	v_exp_f32_e32 v42, v42
	s_waitcnt lgkmcnt(7)
	v_mfma_f32_32x32x16_bf16 v[48:63], v[230:233], v[78:81], v[48:63]
	ds_read_b128 v[230:233], v147 offset:24576
	v_exp_f32_e32 v43, v43
	v_sub_f32_e32 v44, v44, v217
	v_sub_f32_e32 v45, v45, v217
	v_sub_f32_e32 v46, v46, v217
	v_sub_f32_e32 v47, v47, v217
	v_exp_f32_e32 v44, v44
	s_waitcnt lgkmcnt(7)
	v_mfma_f32_32x32x16_bf16 v[48:63], v[234:237], v[82:85], v[48:63]
	ds_read_b128 v[234:237], v242 offset:16384
	v_exp_f32_e32 v45, v45
	v_exp_f32_e32 v46, v46
	v_exp_f32_e32 v47, v47
	v_add_f32_e32 v153, v96, v40
	v_add_f32_e32 v152, v41, v42
	v_add_f32_e32 v153, v153, v43
	s_waitcnt lgkmcnt(7)
	v_mfma_f32_32x32x16_bf16 v[48:63], v[238:241], v[86:89], v[48:63]
	ds_read_b128 v[238:241], v246 offset:16384
	v_add_f32_e32 v153, v153, v44
	v_add_f32_e32 v152, v152, v45
	v_add_f32_e32 v153, v153, v46
	v_add_f32_e32 v152, v152, v47
	v_cvt_pk_bf16_f32 v40, v40, v41
	v_cvt_pk_bf16_f32 v41, v42, v43
	v_cvt_pk_bf16_f32 v42, v44, v45
	v_cvt_pk_bf16_f32 v43, v46, v47
	s_nop 1
	s_waitcnt lgkmcnt(7)
	v_mfma_f32_32x32x16_bf16 v[0:15], v[90:93], v[40:43], v[0:15]
	v_sub_f32_e32 v32, v32, v217
	v_sub_f32_e32 v33, v33, v217
	v_sub_f32_e32 v34, v34, v217
	v_sub_f32_e32 v35, v35, v217
	v_exp_f32_e32 v32, v32
	v_exp_f32_e32 v33, v33
	v_exp_f32_e32 v34, v34
	v_exp_f32_e32 v35, v35
	s_waitcnt lgkmcnt(6)
	v_mfma_f32_32x32x16_bf16 v[16:31], v[148:151], v[40:43], v[16:31]
	v_sub_f32_e32 v36, v36, v217
	v_sub_f32_e32 v37, v37, v217
	v_sub_f32_e32 v38, v38, v217
	v_sub_f32_e32 v39, v39, v217
	v_exp_f32_e32 v36, v36
	v_exp_f32_e32 v37, v37
	v_exp_f32_e32 v38, v38
	v_exp_f32_e32 v39, v39
	v_add_f32_e32 v153, v153, v32
	v_add_f32_e32 v152, v152, v33
	v_add_f32_e32 v153, v153, v34
	v_add_f32_e32 v152, v152, v35
	v_add_f32_e32 v153, v153, v36
	v_add_f32_e32 v152, v152, v37
	v_add_f32_e32 v153, v153, v38
	v_add_f32_e32 v152, v152, v39
	v_cvt_pk_bf16_f32 v32, v32, v33
	v_cvt_pk_bf16_f32 v33, v34, v35
	v_cvt_pk_bf16_f32 v34, v36, v37
	v_cvt_pk_bf16_f32 v35, v38, v39
	v_add_f32_e32 v96, v153, v152
	s_nop 0
	s_waitcnt lgkmcnt(1)
	v_mfma_f32_32x32x16_bf16 v[0:15], v[234:237], v[32:35], v[0:15]
	ds_read_b128 v[234:237], v200 offset:24576
	s_waitcnt lgkmcnt(1)
	v_mfma_f32_32x32x16_bf16 v[16:31], v[238:241], v[32:35], v[16:31]
	ds_read_b128 v[238:241], v201 offset:24576
	ds_read_b128 v[90:93], v245 offset:16384
	ds_read_b128 v[148:151], v249 offset:16384
	v_mfma_f32_32x32x16_bf16 v[32:47], v[218:221], v[66:69], 0
	ds_read_b128 v[218:221], v94 offset:32768
	v_max3_f32 v152, v48, v49, v50
	v_max3_f32 v153, v51, v52, v53
	v_max3_f32 v152, v152, v54, v55
	v_max3_f32 v153, v153, v56, v57
	v_max3_f32 v152, v152, v58, v59
	v_max3_f32 v153, v153, v60, v61
	v_mfma_f32_32x32x16_bf16 v[32:47], v[222:225], v[70:73], v[32:47]
	ds_read_b128 v[222:225], v95 offset:32768
	v_max3_f32 v152, v152, v62, v63
	v_max_f32_e32 v152, v152, v153
	v_mov_b32_e32 v153, v152
	s_nop 1
	v_permlane32_swap_b32_e32 v153, v152
	v_max_f32_e32 v152, v152, v153
	v_cmp_lt_f32_e32 vcc, v252, v152
	s_cbranch_vccnz .Lam_c0u1_rare
.Lam_c0u1_back:
	v_sub_f32_e32 v56, v56, v217
	v_mfma_f32_32x32x16_bf16 v[32:47], v[226:229], v[74:77], v[32:47]
	ds_read_b128 v[226:229], v97 offset:32768
	v_sub_f32_e32 v57, v57, v217
	v_sub_f32_e32 v58, v58, v217
	v_sub_f32_e32 v59, v59, v217
	v_exp_f32_e32 v56, v56
	v_exp_f32_e32 v57, v57
	v_exp_f32_e32 v58, v58
	v_mfma_f32_32x32x16_bf16 v[32:47], v[230:233], v[78:81], v[32:47]
	ds_read_b128 v[230:233], v147 offset:32768
	v_exp_f32_e32 v59, v59
	v_sub_f32_e32 v60, v60, v217
	v_sub_f32_e32 v61, v61, v217
	v_sub_f32_e32 v62, v62, v217
	v_sub_f32_e32 v63, v63, v217
	v_exp_f32_e32 v60, v60
	s_waitcnt lgkmcnt(7)
	v_mfma_f32_32x32x16_bf16 v[32:47], v[234:237], v[82:85], v[32:47]
	ds_read_b128 v[234:237], v244 offset:16384
	v_exp_f32_e32 v61, v61
	v_exp_f32_e32 v62, v62
	v_exp_f32_e32 v63, v63
	v_add_f32_e32 v153, v96, v56
	v_add_f32_e32 v152, v57, v58
	v_add_f32_e32 v153, v153, v59
	s_waitcnt lgkmcnt(7)
	v_mfma_f32_32x32x16_bf16 v[32:47], v[238:241], v[86:89], v[32:47]
	ds_read_b128 v[238:241], v248 offset:16384
	v_add_f32_e32 v153, v153, v60
	v_add_f32_e32 v152, v152, v61
	v_add_f32_e32 v153, v153, v62
	v_add_f32_e32 v152, v152, v63
	v_cvt_pk_bf16_f32 v56, v56, v57
	v_cvt_pk_bf16_f32 v57, v58, v59
	v_cvt_pk_bf16_f32 v58, v60, v61
	v_cvt_pk_bf16_f32 v59, v62, v63
	s_nop 1
	s_waitcnt lgkmcnt(7)
	v_mfma_f32_32x32x16_bf16 v[0:15], v[90:93], v[56:59], v[0:15]
	v_sub_f32_e32 v48, v48, v217
	v_sub_f32_e32 v49, v49, v217
	v_sub_f32_e32 v50, v50, v217
	v_sub_f32_e32 v51, v51, v217
	v_exp_f32_e32 v48, v48
	v_exp_f32_e32 v49, v49
	v_exp_f32_e32 v50, v50
	v_exp_f32_e32 v51, v51
	s_waitcnt lgkmcnt(6)
	v_mfma_f32_32x32x16_bf16 v[16:31], v[148:151], v[56:59], v[16:31]
	v_sub_f32_e32 v52, v52, v217
	v_sub_f32_e32 v53, v53, v217
	v_sub_f32_e32 v54, v54, v217
	v_sub_f32_e32 v55, v55, v217
	v_exp_f32_e32 v52, v52
	v_exp_f32_e32 v53, v53
	v_exp_f32_e32 v54, v54
	v_exp_f32_e32 v55, v55
	v_add_f32_e32 v153, v153, v48
	v_add_f32_e32 v152, v152, v49
	v_add_f32_e32 v153, v153, v50
	v_add_f32_e32 v152, v152, v51
	v_add_f32_e32 v153, v153, v52
	v_add_f32_e32 v152, v152, v53
	v_add_f32_e32 v153, v153, v54
	v_add_f32_e32 v152, v152, v55
	v_cvt_pk_bf16_f32 v48, v48, v49
	v_cvt_pk_bf16_f32 v49, v50, v51
	v_cvt_pk_bf16_f32 v50, v52, v53
	v_cvt_pk_bf16_f32 v51, v54, v55
	v_add_f32_e32 v96, v153, v152
	s_nop 0
	s_waitcnt lgkmcnt(1)
	v_mfma_f32_32x32x16_bf16 v[0:15], v[234:237], v[48:51], v[0:15]
	ds_read_b128 v[234:237], v200 offset:32768
	s_waitcnt lgkmcnt(1)
	v_mfma_f32_32x32x16_bf16 v[16:31], v[238:241], v[48:51], v[16:31]
	ds_read_b128 v[238:241], v201 offset:32768
	v_add_u32_e32 v94, 0xc000, v94
	v_add_u32_e32 v95, 0xc000, v95
	v_add_u32_e32 v97, 0xc000, v97
	v_add_u32_e32 v147, 0xc000, v147
	v_add_u32_e32 v200, 0xc000, v200
	v_add_u32_e32 v201, 0xc000, v201
	ds_read_b128 v[90:93], v243 offset:40960
	ds_read_b128 v[148:151], v247 offset:40960
	v_mfma_f32_32x32x16_bf16 v[48:63], v[218:221], v[66:69], 0
	ds_read_b128 v[218:221], v94
	v_max3_f32 v152, v32, v33, v34
	v_max3_f32 v153, v35, v36, v37
	v_max3_f32 v152, v152, v38, v39
	v_max3_f32 v153, v153, v40, v41
	v_max3_f32 v152, v152, v42, v43
	v_max3_f32 v153, v153, v44, v45
	v_mfma_f32_32x32x16_bf16 v[48:63], v[222:225], v[70:73], v[48:63]
	ds_read_b128 v[222:225], v95
	v_max3_f32 v152, v152, v46, v47
	v_max_f32_e32 v152, v152, v153
	v_mov_b32_e32 v153, v152
	s_nop 1
	v_permlane32_swap_b32_e32 v153, v152
	v_max_f32_e32 v152, v152, v153
	v_cmp_lt_f32_e32 vcc, v252, v152
	s_cbranch_vccnz .Lam_c0u2_rare
.Lam_c0u2_back:
	v_sub_f32_e32 v40, v40, v217
	v_mfma_f32_32x32x16_bf16 v[48:63], v[226:229], v[74:77], v[48:63]
	ds_read_b128 v[226:229], v97
	v_sub_f32_e32 v41, v41, v217
	v_sub_f32_e32 v42, v42, v217
	v_sub_f32_e32 v43, v43, v217
	v_exp_f32_e32 v40, v40
	v_exp_f32_e32 v41, v41
	v_exp_f32_e32 v42, v42
	v_mfma_f32_32x32x16_bf16 v[48:63], v[230:233], v[78:81], v[48:63]
	ds_read_b128 v[230:233], v147
	v_exp_f32_e32 v43, v43
	v_sub_f32_e32 v44, v44, v217
	v_sub_f32_e32 v45, v45, v217
	v_sub_f32_e32 v46, v46, v217
	v_sub_f32_e32 v47, v47, v217
	v_exp_f32_e32 v44, v44
	s_waitcnt lgkmcnt(7)
	v_mfma_f32_32x32x16_bf16 v[48:63], v[234:237], v[82:85], v[48:63]
	ds_read_b128 v[234:237], v242 offset:40960
	v_exp_f32_e32 v45, v45
	v_exp_f32_e32 v46, v46
	v_exp_f32_e32 v47, v47
	v_add_f32_e32 v153, v96, v40
	v_add_f32_e32 v152, v41, v42
	v_add_f32_e32 v153, v153, v43
	s_waitcnt lgkmcnt(7)
	v_mfma_f32_32x32x16_bf16 v[48:63], v[238:241], v[86:89], v[48:63]
	ds_read_b128 v[238:241], v246 offset:40960
	v_add_f32_e32 v153, v153, v44
	v_add_f32_e32 v152, v152, v45
	v_add_f32_e32 v153, v153, v46
	v_add_f32_e32 v152, v152, v47
	v_cvt_pk_bf16_f32 v40, v40, v41
	v_cvt_pk_bf16_f32 v41, v42, v43
	v_cvt_pk_bf16_f32 v42, v44, v45
	v_cvt_pk_bf16_f32 v43, v46, v47
	s_nop 1
	s_waitcnt lgkmcnt(7)
	v_mfma_f32_32x32x16_bf16 v[0:15], v[90:93], v[40:43], v[0:15]
	v_sub_f32_e32 v32, v32, v217
	v_sub_f32_e32 v33, v33, v217
	v_sub_f32_e32 v34, v34, v217
	v_sub_f32_e32 v35, v35, v217
	v_exp_f32_e32 v32, v32
	v_exp_f32_e32 v33, v33
	v_exp_f32_e32 v34, v34
	v_exp_f32_e32 v35, v35
	s_waitcnt lgkmcnt(6)
	v_mfma_f32_32x32x16_bf16 v[16:31], v[148:151], v[40:43], v[16:31]
	v_sub_f32_e32 v36, v36, v217
	v_sub_f32_e32 v37, v37, v217
	v_sub_f32_e32 v38, v38, v217
	v_sub_f32_e32 v39, v39, v217
	v_exp_f32_e32 v36, v36
	v_exp_f32_e32 v37, v37
	v_exp_f32_e32 v38, v38
	v_exp_f32_e32 v39, v39
	v_add_f32_e32 v153, v153, v32
	v_add_f32_e32 v152, v152, v33
	v_add_f32_e32 v153, v153, v34
	v_add_f32_e32 v152, v152, v35
	v_add_f32_e32 v153, v153, v36
	v_add_f32_e32 v152, v152, v37
	v_add_f32_e32 v153, v153, v38
	v_add_f32_e32 v152, v152, v39
	v_cvt_pk_bf16_f32 v32, v32, v33
	v_cvt_pk_bf16_f32 v33, v34, v35
	v_cvt_pk_bf16_f32 v34, v36, v37
	v_cvt_pk_bf16_f32 v35, v38, v39
	v_add_f32_e32 v96, v153, v152
	s_nop 0
	s_waitcnt lgkmcnt(1)
	v_mfma_f32_32x32x16_bf16 v[0:15], v[234:237], v[32:35], v[0:15]
	ds_read_b128 v[234:237], v200
	s_waitcnt lgkmcnt(1)
	v_mfma_f32_32x32x16_bf16 v[16:31], v[238:241], v[32:35], v[16:31]
	ds_read_b128 v[238:241], v201
	ds_read_b128 v[90:93], v245 offset:40960
	ds_read_b128 v[148:151], v249 offset:40960
	v_mfma_f32_32x32x16_bf16 v[32:47], v[218:221], v[66:69], 0
	ds_read_b128 v[218:221], v94 offset:8192
	v_max3_f32 v152, v48, v49, v50
	v_max3_f32 v153, v51, v52, v53
	v_max3_f32 v152, v152, v54, v55
	v_max3_f32 v153, v153, v56, v57
	v_max3_f32 v152, v152, v58, v59
	v_max3_f32 v153, v153, v60, v61
	v_mfma_f32_32x32x16_bf16 v[32:47], v[222:225], v[70:73], v[32:47]
	ds_read_b128 v[222:225], v95 offset:8192
	v_max3_f32 v152, v152, v62, v63
	v_max_f32_e32 v152, v152, v153
	v_mov_b32_e32 v153, v152
	s_nop 1
	v_permlane32_swap_b32_e32 v153, v152
	v_max_f32_e32 v152, v152, v153
	v_cmp_lt_f32_e32 vcc, v252, v152
	s_cbranch_vccnz .Lam_c0u3_rare
.Lam_c0u3_back:
	v_sub_f32_e32 v56, v56, v217
	v_mfma_f32_32x32x16_bf16 v[32:47], v[226:229], v[74:77], v[32:47]
	ds_read_b128 v[226:229], v97 offset:8192
	v_sub_f32_e32 v57, v57, v217
	v_sub_f32_e32 v58, v58, v217
	v_sub_f32_e32 v59, v59, v217
	v_exp_f32_e32 v56, v56
	v_exp_f32_e32 v57, v57
	v_exp_f32_e32 v58, v58
	v_mfma_f32_32x32x16_bf16 v[32:47], v[230:233], v[78:81], v[32:47]
	ds_read_b128 v[230:233], v147 offset:8192
	v_exp_f32_e32 v59, v59
	v_sub_f32_e32 v60, v60, v217
	v_sub_f32_e32 v61, v61, v217
	v_sub_f32_e32 v62, v62, v217
	v_sub_f32_e32 v63, v63, v217
	v_exp_f32_e32 v60, v60
	s_waitcnt lgkmcnt(7)
	v_mfma_f32_32x32x16_bf16 v[32:47], v[234:237], v[82:85], v[32:47]
	ds_read_b128 v[234:237], v244 offset:40960
	v_exp_f32_e32 v61, v61
	v_exp_f32_e32 v62, v62
	v_exp_f32_e32 v63, v63
	v_add_f32_e32 v153, v96, v56
	v_add_f32_e32 v152, v57, v58
	v_add_f32_e32 v153, v153, v59
	s_waitcnt lgkmcnt(7)
	v_mfma_f32_32x32x16_bf16 v[32:47], v[238:241], v[86:89], v[32:47]
	ds_read_b128 v[238:241], v248 offset:40960
	v_add_f32_e32 v153, v153, v60
	v_add_f32_e32 v152, v152, v61
	v_add_f32_e32 v153, v153, v62
	v_add_f32_e32 v152, v152, v63
	v_cvt_pk_bf16_f32 v56, v56, v57
	v_cvt_pk_bf16_f32 v57, v58, v59
	v_cvt_pk_bf16_f32 v58, v60, v61
	v_cvt_pk_bf16_f32 v59, v62, v63
	s_nop 1
	s_waitcnt lgkmcnt(7)
	v_mfma_f32_32x32x16_bf16 v[0:15], v[90:93], v[56:59], v[0:15]
	v_sub_f32_e32 v48, v48, v217
	v_sub_f32_e32 v49, v49, v217
	v_sub_f32_e32 v50, v50, v217
	v_sub_f32_e32 v51, v51, v217
	v_exp_f32_e32 v48, v48
	v_exp_f32_e32 v49, v49
	v_exp_f32_e32 v50, v50
	v_exp_f32_e32 v51, v51
	s_waitcnt lgkmcnt(6)
	v_mfma_f32_32x32x16_bf16 v[16:31], v[148:151], v[56:59], v[16:31]
	v_sub_f32_e32 v52, v52, v217
	v_sub_f32_e32 v53, v53, v217
	v_sub_f32_e32 v54, v54, v217
	v_sub_f32_e32 v55, v55, v217
	v_exp_f32_e32 v52, v52
	v_exp_f32_e32 v53, v53
	v_exp_f32_e32 v54, v54
	v_exp_f32_e32 v55, v55
	v_add_f32_e32 v153, v153, v48
	v_add_f32_e32 v152, v152, v49
	v_add_f32_e32 v153, v153, v50
	v_add_f32_e32 v152, v152, v51
	v_add_f32_e32 v153, v153, v52
	v_add_f32_e32 v152, v152, v53
	v_add_f32_e32 v153, v153, v54
	v_add_f32_e32 v152, v152, v55
	v_cvt_pk_bf16_f32 v48, v48, v49
	v_cvt_pk_bf16_f32 v49, v50, v51
	v_cvt_pk_bf16_f32 v50, v52, v53
	v_cvt_pk_bf16_f32 v51, v54, v55
	v_add_f32_e32 v96, v153, v152
	s_nop 0
	s_waitcnt lgkmcnt(1)
	v_mfma_f32_32x32x16_bf16 v[0:15], v[234:237], v[48:51], v[0:15]
	ds_read_b128 v[234:237], v200 offset:8192
	s_waitcnt lgkmcnt(1)
	v_mfma_f32_32x32x16_bf16 v[16:31], v[238:241], v[48:51], v[16:31]
	ds_read_b128 v[238:241], v201 offset:8192
	s_add_i32 s81, s81, -1
	s_cmp_eq_u32 s81, 0
	s_cbranch_scc1 .Lam_exit
	s_waitcnt vmcnt(3)
	s_barrier
	s_add_u32 m0, s82, 0x0
	v_lshl_add_u64 v[152:153], v[142:143], 0, s[84:85]
	global_load_lds_dwordx4 v[152:153], off
	s_add_u32 m0, s82, 0x400
	v_lshl_add_u64 v[152:153], v[144:145], 0, s[84:85]
	global_load_lds_dwordx4 v[152:153], off
	s_add_u32 m0, s83, 0x4000
	v_lshl_add_u64 v[152:153], v[140:141], 0, s[86:87]
	global_load_lds_dwordx4 v[152:153], off
	s_add_u32 m0, s82, 0x6000
	v_lshl_add_u64 v[152:153], v[142:143], 0, s[88:89]
	global_load_lds_dwordx4 v[152:153], off
	s_add_u32 m0, s82, 0x6400
	v_lshl_add_u64 v[152:153], v[144:145], 0, s[88:89]
	global_load_lds_dwordx4 v[152:153], off
	s_add_u32 m0, s83, 0xa000
	v_lshl_add_u64 v[152:153], v[140:141], 0, s[90:91]
	global_load_lds_dwordx4 v[152:153], off
	s_add_u32 s84, s84, 0x30000
	s_addc_u32 s85, s85, 0
	s_add_u32 s88, s88, 0x30000
	s_addc_u32 s89, s89, 0
	s_add_u32 s86, s86, 0x100
	s_addc_u32 s87, s87, 0
	s_add_u32 s90, s90, 0x100
	s_addc_u32 s91, s91, 0
	v_add_u32_e32 v242, 0xc000, v242
	v_add_u32_e32 v243, 0xc000, v243
	v_add_u32_e32 v244, 0xc000, v244
	v_add_u32_e32 v245, 0xc000, v245
	v_add_u32_e32 v246, 0xc000, v246
	v_add_u32_e32 v247, 0xc000, v247
	v_add_u32_e32 v248, 0xc000, v248
	v_add_u32_e32 v249, 0xc000, v249
	ds_read_b128 v[90:93], v243 offset:16384
	ds_read_b128 v[148:151], v247 offset:16384
	v_mfma_f32_32x32x16_bf16 v[48:63], v[218:221], v[66:69], 0
	ds_read_b128 v[218:221], v94 offset:24576
	v_max3_f32 v152, v32, v33, v34
	v_max3_f32 v153, v35, v36, v37
	v_max3_f32 v152, v152, v38, v39
	v_max3_f32 v153, v153, v40, v41
	v_max3_f32 v152, v152, v42, v43
	v_max3_f32 v153, v153, v44, v45
	v_mfma_f32_32x32x16_bf16 v[48:63], v[222:225], v[70:73], v[48:63]
	ds_read_b128 v[222:225], v95 offset:24576
	v_max3_f32 v152, v152, v46, v47
	v_max_f32_e32 v152, v152, v153
	v_mov_b32_e32 v153, v152
	s_nop 1
	v_permlane32_swap_b32_e32 v153, v152
	v_max_f32_e32 v152, v152, v153
	v_cmp_lt_f32_e32 vcc, v252, v152
	s_cbranch_vccnz .Lam_c1u0_rare
.Lam_c1u0_back:
	v_sub_f32_e32 v40, v40, v217
	v_mfma_f32_32x32x16_bf16 v[48:63], v[226:229], v[74:77], v[48:63]
	ds_read_b128 v[226:229], v97 offset:24576
	v_sub_f32_e32 v41, v41, v217
	v_sub_f32_e32 v42, v42, v217
	v_sub_f32_e32 v43, v43, v217
	v_exp_f32_e32 v40, v40
	v_exp_f32_e32 v41, v41
	v_exp_f32_e32 v42, v42
	v_mfma_f32_32x32x16_bf16 v[48:63], v[230:233], v[78:81], v[48:63]
	ds_read_b128 v[230:233], v147 offset:24576
	v_exp_f32_e32 v43, v43
	v_sub_f32_e32 v44, v44, v217
	v_sub_f32_e32 v45, v45, v217
	v_sub_f32_e32 v46, v46, v217
	v_sub_f32_e32 v47, v47, v217
	v_exp_f32_e32 v44, v44
	s_waitcnt lgkmcnt(7)
	v_mfma_f32_32x32x16_bf16 v[48:63], v[234:237], v[82:85], v[48:63]
	ds_read_b128 v[234:237], v242 offset:16384
	v_exp_f32_e32 v45, v45
	v_exp_f32_e32 v46, v46
	v_exp_f32_e32 v47, v47
	v_add_f32_e32 v153, v96, v40
	v_add_f32_e32 v152, v41, v42
	v_add_f32_e32 v153, v153, v43
	s_waitcnt lgkmcnt(7)
	v_mfma_f32_32x32x16_bf16 v[48:63], v[238:241], v[86:89], v[48:63]
	ds_read_b128 v[238:241], v246 offset:16384
	v_add_f32_e32 v153, v153, v44
	v_add_f32_e32 v152, v152, v45
	v_add_f32_e32 v153, v153, v46
	v_add_f32_e32 v152, v152, v47
	v_cvt_pk_bf16_f32 v40, v40, v41
	v_cvt_pk_bf16_f32 v41, v42, v43
	v_cvt_pk_bf16_f32 v42, v44, v45
	v_cvt_pk_bf16_f32 v43, v46, v47
	s_nop 1
	s_waitcnt lgkmcnt(7)
	v_mfma_f32_32x32x16_bf16 v[0:15], v[90:93], v[40:43], v[0:15]
	v_sub_f32_e32 v32, v32, v217
	v_sub_f32_e32 v33, v33, v217
	v_sub_f32_e32 v34, v34, v217
	v_sub_f32_e32 v35, v35, v217
	v_exp_f32_e32 v32, v32
	v_exp_f32_e32 v33, v33
	v_exp_f32_e32 v34, v34
	v_exp_f32_e32 v35, v35
	s_waitcnt lgkmcnt(6)
	v_mfma_f32_32x32x16_bf16 v[16:31], v[148:151], v[40:43], v[16:31]
	v_sub_f32_e32 v36, v36, v217
	v_sub_f32_e32 v37, v37, v217
	v_sub_f32_e32 v38, v38, v217
	v_sub_f32_e32 v39, v39, v217
	v_exp_f32_e32 v36, v36
	v_exp_f32_e32 v37, v37
	v_exp_f32_e32 v38, v38
	v_exp_f32_e32 v39, v39
	v_add_f32_e32 v153, v153, v32
	v_add_f32_e32 v152, v152, v33
	v_add_f32_e32 v153, v153, v34
	v_add_f32_e32 v152, v152, v35
	v_add_f32_e32 v153, v153, v36
	v_add_f32_e32 v152, v152, v37
	v_add_f32_e32 v153, v153, v38
	v_add_f32_e32 v152, v152, v39
	v_cvt_pk_bf16_f32 v32, v32, v33
	v_cvt_pk_bf16_f32 v33, v34, v35
	v_cvt_pk_bf16_f32 v34, v36, v37
	v_cvt_pk_bf16_f32 v35, v38, v39
	v_add_f32_e32 v96, v153, v152
	s_nop 0
	s_waitcnt lgkmcnt(1)
	v_mfma_f32_32x32x16_bf16 v[0:15], v[234:237], v[32:35], v[0:15]
	ds_read_b128 v[234:237], v200 offset:24576
	s_waitcnt lgkmcnt(1)
	v_mfma_f32_32x32x16_bf16 v[16:31], v[238:241], v[32:35], v[16:31]
	ds_read_b128 v[238:241], v201 offset:24576
	ds_read_b128 v[90:93], v245 offset:16384
	ds_read_b128 v[148:151], v249 offset:16384
	v_mfma_f32_32x32x16_bf16 v[32:47], v[218:221], v[66:69], 0
	ds_read_b128 v[218:221], v94 offset:32768
	v_max3_f32 v152, v48, v49, v50
	v_max3_f32 v153, v51, v52, v53
	v_max3_f32 v152, v152, v54, v55
	v_max3_f32 v153, v153, v56, v57
	v_max3_f32 v152, v152, v58, v59
	v_max3_f32 v153, v153, v60, v61
	v_mfma_f32_32x32x16_bf16 v[32:47], v[222:225], v[70:73], v[32:47]
	ds_read_b128 v[222:225], v95 offset:32768
	v_max3_f32 v152, v152, v62, v63
	v_max_f32_e32 v152, v152, v153
	v_mov_b32_e32 v153, v152
	s_nop 1
	v_permlane32_swap_b32_e32 v153, v152
	v_max_f32_e32 v152, v152, v153
	v_cmp_lt_f32_e32 vcc, v252, v152
	s_cbranch_vccnz .Lam_c1u1_rare

.Lam_c1u3_back:
	v_sub_f32_e32 v56, v56, v217
	v_mfma_f32_32x32x16_bf16 v[32:47], v[226:229], v[74:77], v[32:47]
	ds_read_b128 v[226:229], v97 offset:8192
	v_sub_f32_e32 v57, v57, v217
	v_sub_f32_e32 v58, v58, v217
	v_sub_f32_e32 v59, v59, v217
	v_exp_f32_e32 v56, v56
	v_exp_f32_e32 v57, v57
	v_exp_f32_e32 v58, v58
	v_mfma_f32_32x32x16_bf16 v[32:47], v[230:233], v[78:81], v[32:47]
	ds_read_b128 v[230:233], v147 offset:8192
	v_exp_f32_e32 v59, v59
	v_sub_f32_e32 v60, v60, v217
	v_sub_f32_e32 v61, v61, v217
	v_sub_f32_e32 v62, v62, v217
	v_sub_f32_e32 v63, v63, v217
	v_exp_f32_e32 v60, v60
	s_waitcnt lgkmcnt(7)
	v_mfma_f32_32x32x16_bf16 v[32:47], v[234:237], v[82:85], v[32:47]
	ds_read_b128 v[234:237], v244 offset:40960
	v_exp_f32_e32 v61, v61
	v_exp_f32_e32 v62, v62
	v_exp_f32_e32 v63, v63
	v_add_f32_e32 v153, v96, v56
	v_add_f32_e32 v152, v57, v58
	v_add_f32_e32 v153, v153, v59
	s_waitcnt lgkmcnt(7)
	v_mfma_f32_32x32x16_bf16 v[32:47], v[238:241], v[86:89], v[32:47]
	ds_read_b128 v[238:241], v248 offset:40960
	v_add_f32_e32 v153, v153, v60
	v_add_f32_e32 v152, v152, v61
	v_add_f32_e32 v153, v153, v62
	v_add_f32_e32 v152, v152, v63
	v_cvt_pk_bf16_f32 v56, v56, v57
	v_cvt_pk_bf16_f32 v57, v58, v59
	v_cvt_pk_bf16_f32 v58, v60, v61
	v_cvt_pk_bf16_f32 v59, v62, v63
	s_nop 1
	s_waitcnt lgkmcnt(7)
	v_mfma_f32_32x32x16_bf16 v[0:15], v[90:93], v[56:59], v[0:15]
	v_sub_f32_e32 v48, v48, v217
	v_sub_f32_e32 v49, v49, v217
	v_sub_f32_e32 v50, v50, v217
	v_sub_f32_e32 v51, v51, v217
	v_exp_f32_e32 v48, v48
	v_exp_f32_e32 v49, v49
	v_exp_f32_e32 v50, v50
	v_exp_f32_e32 v51, v51
	s_waitcnt lgkmcnt(6)
	v_mfma_f32_32x32x16_bf16 v[16:31], v[148:151], v[56:59], v[16:31]
	v_sub_f32_e32 v52, v52, v217
	v_sub_f32_e32 v53, v53, v217
	v_sub_f32_e32 v54, v54, v217
	v_sub_f32_e32 v55, v55, v217
	v_exp_f32_e32 v52, v52
	v_exp_f32_e32 v53, v53
	v_exp_f32_e32 v54, v54
	v_exp_f32_e32 v55, v55
	v_add_f32_e32 v153, v153, v48
	v_add_f32_e32 v152, v152, v49
	v_add_f32_e32 v153, v153, v50
	v_add_f32_e32 v152, v152, v51
	v_add_f32_e32 v153, v153, v52
	v_add_f32_e32 v152, v152, v53
	v_add_f32_e32 v153, v153, v54
	v_add_f32_e32 v152, v152, v55
	v_cvt_pk_bf16_f32 v48, v48, v49
	v_cvt_pk_bf16_f32 v49, v50, v51
	v_cvt_pk_bf16_f32 v50, v52, v53
	v_cvt_pk_bf16_f32 v51, v54, v55
	v_add_f32_e32 v96, v153, v152
	s_nop 0
	s_waitcnt lgkmcnt(1)
	v_mfma_f32_32x32x16_bf16 v[0:15], v[234:237], v[48:51], v[0:15]
	ds_read_b128 v[234:237], v200 offset:8192
	s_waitcnt lgkmcnt(1)
	v_mfma_f32_32x32x16_bf16 v[16:31], v[238:241], v[48:51], v[16:31]
	ds_read_b128 v[238:241], v201 offset:8192
	s_add_i32 s81, s81, -1
	s_cmp_eq_u32 s81, 0
	s_cbranch_scc1 .Lam_exit
	s_waitcnt vmcnt(3)
	s_barrier
	s_add_u32 m0, s82, 0xc000
	v_lshl_add_u64 v[152:153], v[142:143], 0, s[84:85]
	global_load_lds_dwordx4 v[152:153], off
	s_add_u32 m0, s82, 0xc400
	v_lshl_add_u64 v[152:153], v[144:145], 0, s[84:85]
	global_load_lds_dwordx4 v[152:153], off
	s_add_u32 m0, s83, 0x10000
	v_lshl_add_u64 v[152:153], v[140:141], 0, s[86:87]
	global_load_lds_dwordx4 v[152:153], off
	s_add_u32 m0, s82, 0x12000
	v_lshl_add_u64 v[152:153], v[142:143], 0, s[88:89]
	global_load_lds_dwordx4 v[152:153], off
	s_add_u32 m0, s82, 0x12400
	v_lshl_add_u64 v[152:153], v[144:145], 0, s[88:89]
	global_load_lds_dwordx4 v[152:153], off
	s_add_u32 m0, s83, 0x16000
	v_lshl_add_u64 v[152:153], v[140:141], 0, s[90:91]
	global_load_lds_dwordx4 v[152:153], off
	s_add_u32 s84, s84, 0x30000
	s_addc_u32 s85, s85, 0
	s_add_u32 s88, s88, 0x30000
	s_addc_u32 s89, s89, 0
	s_add_u32 s86, s86, 0x100
	s_addc_u32 s87, s87, 0
	s_add_u32 s90, s90, 0x100
	s_addc_u32 s91, s91, 0
	v_add_u32_e32 v242, 0xc000, v242
	v_add_u32_e32 v243, 0xc000, v243
	v_add_u32_e32 v244, 0xc000, v244
	v_add_u32_e32 v245, 0xc000, v245
	v_add_u32_e32 v246, 0xc000, v246
	v_add_u32_e32 v247, 0xc000, v247
	v_add_u32_e32 v248, 0xc000, v248
	v_add_u32_e32 v249, 0xc000, v249
	ds_read_b128 v[90:93], v243 offset:16384
	ds_read_b128 v[148:151], v247 offset:16384
	v_mfma_f32_32x32x16_bf16 v[48:63], v[218:221], v[66:69], 0
	ds_read_b128 v[218:221], v94 offset:24576
	v_max3_f32 v152, v32, v33, v34
	v_max3_f32 v153, v35, v36, v37
	v_max3_f32 v152, v152, v38, v39
	v_max3_f32 v153, v153, v40, v41
	v_max3_f32 v152, v152, v42, v43
	v_max3_f32 v153, v153, v44, v45
	v_mfma_f32_32x32x16_bf16 v[48:63], v[222:225], v[70:73], v[48:63]
	ds_read_b128 v[222:225], v95 offset:24576
	v_max3_f32 v152, v152, v46, v47
	v_max_f32_e32 v152, v152, v153
	v_mov_b32_e32 v153, v152
	s_nop 1
	v_permlane32_swap_b32_e32 v153, v152
	v_max_f32_e32 v152, v152, v153
	v_cmp_lt_f32_e32 vcc, v252, v152
	s_cbranch_vccnz .Lam_c2u0_rare

.Lam_c2u1_back:
	v_sub_f32_e32 v56, v56, v217
	v_mfma_f32_32x32x16_bf16 v[32:47], v[226:229], v[74:77], v[32:47]
	ds_read_b128 v[226:229], v97 offset:32768
	v_sub_f32_e32 v57, v57, v217
	v_sub_f32_e32 v58, v58, v217
	v_sub_f32_e32 v59, v59, v217
	v_exp_f32_e32 v56, v56
	v_exp_f32_e32 v57, v57
	v_exp_f32_e32 v58, v58
	v_mfma_f32_32x32x16_bf16 v[32:47], v[230:233], v[78:81], v[32:47]
	ds_read_b128 v[230:233], v147 offset:32768
	v_exp_f32_e32 v59, v59
	v_sub_f32_e32 v60, v60, v217
	v_sub_f32_e32 v61, v61, v217
	v_sub_f32_e32 v62, v62, v217
	v_sub_f32_e32 v63, v63, v217
	v_exp_f32_e32 v60, v60
	s_waitcnt lgkmcnt(7)
	v_mfma_f32_32x32x16_bf16 v[32:47], v[234:237], v[82:85], v[32:47]
	ds_read_b128 v[234:237], v244 offset:16384
	v_exp_f32_e32 v61, v61
	v_exp_f32_e32 v62, v62
	v_exp_f32_e32 v63, v63
	v_add_f32_e32 v153, v96, v56
	v_add_f32_e32 v152, v57, v58
	v_add_f32_e32 v153, v153, v59
	s_waitcnt lgkmcnt(7)
	v_mfma_f32_32x32x16_bf16 v[32:47], v[238:241], v[86:89], v[32:47]
	ds_read_b128 v[238:241], v248 offset:16384
	v_add_f32_e32 v153, v153, v60
	v_add_f32_e32 v152, v152, v61
	v_add_f32_e32 v153, v153, v62
	v_add_f32_e32 v152, v152, v63
	v_cvt_pk_bf16_f32 v56, v56, v57
	v_cvt_pk_bf16_f32 v57, v58, v59
	v_cvt_pk_bf16_f32 v58, v60, v61
	v_cvt_pk_bf16_f32 v59, v62, v63
	s_nop 1
	s_waitcnt lgkmcnt(7)
	v_mfma_f32_32x32x16_bf16 v[0:15], v[90:93], v[56:59], v[0:15]
	v_sub_f32_e32 v48, v48, v217
	v_sub_f32_e32 v49, v49, v217
	v_sub_f32_e32 v50, v50, v217
	v_sub_f32_e32 v51, v51, v217
	v_exp_f32_e32 v48, v48
	v_exp_f32_e32 v49, v49
	v_exp_f32_e32 v50, v50
	v_exp_f32_e32 v51, v51
	s_waitcnt lgkmcnt(6)
	v_mfma_f32_32x32x16_bf16 v[16:31], v[148:151], v[56:59], v[16:31]
	v_sub_f32_e32 v52, v52, v217
	v_sub_f32_e32 v53, v53, v217
	v_sub_f32_e32 v54, v54, v217
	v_sub_f32_e32 v55, v55, v217
	v_exp_f32_e32 v52, v52
	v_exp_f32_e32 v53, v53
	v_exp_f32_e32 v54, v54
	v_exp_f32_e32 v55, v55
	v_add_f32_e32 v153, v153, v48
	v_add_f32_e32 v152, v152, v49
	v_add_f32_e32 v153, v153, v50
	v_add_f32_e32 v152, v152, v51
	v_add_f32_e32 v153, v153, v52
	v_add_f32_e32 v152, v152, v53
	v_add_f32_e32 v153, v153, v54
	v_add_f32_e32 v152, v152, v55
	v_cvt_pk_bf16_f32 v48, v48, v49
	v_cvt_pk_bf16_f32 v49, v50, v51
	v_cvt_pk_bf16_f32 v50, v52, v53
	v_cvt_pk_bf16_f32 v51, v54, v55
	v_add_f32_e32 v96, v153, v152
	s_nop 0
	s_waitcnt lgkmcnt(1)
	v_mfma_f32_32x32x16_bf16 v[0:15], v[234:237], v[48:51], v[0:15]
	ds_read_b128 v[234:237], v200 offset:32768
	s_waitcnt lgkmcnt(1)
	v_mfma_f32_32x32x16_bf16 v[16:31], v[238:241], v[48:51], v[16:31]
	ds_read_b128 v[238:241], v201 offset:32768
	v_add_u32_e32 v94, 0xfffe8000, v94
	v_add_u32_e32 v95, 0xfffe8000, v95
	v_add_u32_e32 v97, 0xfffe8000, v97
	v_add_u32_e32 v147, 0xfffe8000, v147
	v_add_u32_e32 v200, 0xfffe8000, v200
	v_add_u32_e32 v201, 0xfffe8000, v201
	ds_read_b128 v[90:93], v243 offset:40960
	ds_read_b128 v[148:151], v247 offset:40960
	v_mfma_f32_32x32x16_bf16 v[48:63], v[218:221], v[66:69], 0
	ds_read_b128 v[218:221], v94
	v_max3_f32 v152, v32, v33, v34
	v_max3_f32 v153, v35, v36, v37
	v_max3_f32 v152, v152, v38, v39
	v_max3_f32 v153, v153, v40, v41
	v_max3_f32 v152, v152, v42, v43
	v_max3_f32 v153, v153, v44, v45
	v_mfma_f32_32x32x16_bf16 v[48:63], v[222:225], v[70:73], v[48:63]
	ds_read_b128 v[222:225], v95
	v_max3_f32 v152, v152, v46, v47
	v_max_f32_e32 v152, v152, v153
	v_mov_b32_e32 v153, v152
	s_nop 1
	v_permlane32_swap_b32_e32 v153, v152
	v_max_f32_e32 v152, v152, v153
	v_cmp_lt_f32_e32 vcc, v252, v152
	s_cbranch_vccnz .Lam_c2u2_rare

.Lam_c2u3_back:
	v_sub_f32_e32 v56, v56, v217
	v_mfma_f32_32x32x16_bf16 v[32:47], v[226:229], v[74:77], v[32:47]
	ds_read_b128 v[226:229], v97 offset:8192
	v_sub_f32_e32 v57, v57, v217
	v_sub_f32_e32 v58, v58, v217
	v_sub_f32_e32 v59, v59, v217
	v_exp_f32_e32 v56, v56
	v_exp_f32_e32 v57, v57
	v_exp_f32_e32 v58, v58
	v_mfma_f32_32x32x16_bf16 v[32:47], v[230:233], v[78:81], v[32:47]
	ds_read_b128 v[230:233], v147 offset:8192
	v_exp_f32_e32 v59, v59
	v_sub_f32_e32 v60, v60, v217
	v_sub_f32_e32 v61, v61, v217
	v_sub_f32_e32 v62, v62, v217
	v_sub_f32_e32 v63, v63, v217
	v_exp_f32_e32 v60, v60
	s_waitcnt lgkmcnt(7)
	v_mfma_f32_32x32x16_bf16 v[32:47], v[234:237], v[82:85], v[32:47]
	ds_read_b128 v[234:237], v244 offset:40960
	v_exp_f32_e32 v61, v61
	v_exp_f32_e32 v62, v62
	v_exp_f32_e32 v63, v63
	v_add_f32_e32 v153, v96, v56
	v_add_f32_e32 v152, v57, v58
	v_add_f32_e32 v153, v153, v59
	s_waitcnt lgkmcnt(7)
	v_mfma_f32_32x32x16_bf16 v[32:47], v[238:241], v[86:89], v[32:47]
	ds_read_b128 v[238:241], v248 offset:40960
	v_add_f32_e32 v153, v153, v60
	v_add_f32_e32 v152, v152, v61
	v_add_f32_e32 v153, v153, v62
	v_add_f32_e32 v152, v152, v63
	v_cvt_pk_bf16_f32 v56, v56, v57
	v_cvt_pk_bf16_f32 v57, v58, v59
	v_cvt_pk_bf16_f32 v58, v60, v61
	v_cvt_pk_bf16_f32 v59, v62, v63
	s_nop 1
	s_waitcnt lgkmcnt(7)
	v_mfma_f32_32x32x16_bf16 v[0:15], v[90:93], v[56:59], v[0:15]
	v_sub_f32_e32 v48, v48, v217
	v_sub_f32_e32 v49, v49, v217
	v_sub_f32_e32 v50, v50, v217
	v_sub_f32_e32 v51, v51, v217
	v_exp_f32_e32 v48, v48
	v_exp_f32_e32 v49, v49
	v_exp_f32_e32 v50, v50
	v_exp_f32_e32 v51, v51
	s_waitcnt lgkmcnt(6)
	v_mfma_f32_32x32x16_bf16 v[16:31], v[148:151], v[56:59], v[16:31]
	v_sub_f32_e32 v52, v52, v217
	v_sub_f32_e32 v53, v53, v217
	v_sub_f32_e32 v54, v54, v217
	v_sub_f32_e32 v55, v55, v217
	v_exp_f32_e32 v52, v52
	v_exp_f32_e32 v53, v53
	v_exp_f32_e32 v54, v54
	v_exp_f32_e32 v55, v55
	v_add_f32_e32 v153, v153, v48
	v_add_f32_e32 v152, v152, v49
	v_add_f32_e32 v153, v153, v50
	v_add_f32_e32 v152, v152, v51
	v_add_f32_e32 v153, v153, v52
	v_add_f32_e32 v152, v152, v53
	v_add_f32_e32 v153, v153, v54
	v_add_f32_e32 v152, v152, v55
	v_cvt_pk_bf16_f32 v48, v48, v49
	v_cvt_pk_bf16_f32 v49, v50, v51
	v_cvt_pk_bf16_f32 v50, v52, v53
	v_cvt_pk_bf16_f32 v51, v54, v55
	v_add_f32_e32 v96, v153, v152
	s_nop 0
	s_waitcnt lgkmcnt(1)
	v_mfma_f32_32x32x16_bf16 v[0:15], v[234:237], v[48:51], v[0:15]
	ds_read_b128 v[234:237], v200 offset:8192
	s_waitcnt lgkmcnt(1)
	v_mfma_f32_32x32x16_bf16 v[16:31], v[238:241], v[48:51], v[16:31]
	ds_read_b128 v[238:241], v201 offset:8192
	s_add_i32 s81, s81, -1
	s_cmp_eq_u32 s81, 0
	s_cbranch_scc0 .Lam_loop
.Lam_exit:
	s_setprio 0
	s_waitcnt lgkmcnt(0)
	s_branch .LBB0_181
.Lam_c0u0_rare:
	s_nop 0
	v_cndmask_b32_e32 v153, v217, v152, vcc
	v_sub_f32_e32 v152, v217, v153
	v_exp_f32_e32 v152, v152
	v_mov_b32_e32 v217, v153
	v_add_f32_e32 v252, 0x41000000, v153
	v_mul_f32_e32 v96, v96, v152
	v_pk_mul_f32 v[0:1], v[0:1], v[152:153] op_sel_hi:[1,0]
	v_pk_mul_f32 v[2:3], v[2:3], v[152:153] op_sel_hi:[1,0]
	v_pk_mul_f32 v[4:5], v[4:5], v[152:153] op_sel_hi:[1,0]
	v_pk_mul_f32 v[6:7], v[6:7], v[152:153] op_sel_hi:[1,0]
	v_pk_mul_f32 v[8:9], v[8:9], v[152:153] op_sel_hi:[1,0]
	v_pk_mul_f32 v[10:11], v[10:11], v[152:153] op_sel_hi:[1,0]
	v_pk_mul_f32 v[12:13], v[12:13], v[152:153] op_sel_hi:[1,0]
	v_pk_mul_f32 v[14:15], v[14:15], v[152:153] op_sel_hi:[1,0]
	v_pk_mul_f32 v[16:17], v[16:17], v[152:153] op_sel_hi:[1,0]
	v_pk_mul_f32 v[18:19], v[18:19], v[152:153] op_sel_hi:[1,0]
	v_pk_mul_f32 v[20:21], v[20:21], v[152:153] op_sel_hi:[1,0]
	v_pk_mul_f32 v[22:23], v[22:23], v[152:153] op_sel_hi:[1,0]
	v_pk_mul_f32 v[24:25], v[24:25], v[152:153] op_sel_hi:[1,0]
	v_pk_mul_f32 v[26:27], v[26:27], v[152:153] op_sel_hi:[1,0]
	v_pk_mul_f32 v[28:29], v[28:29], v[152:153] op_sel_hi:[1,0]
	v_pk_mul_f32 v[30:31], v[30:31], v[152:153] op_sel_hi:[1,0]
	s_branch .Lam_c0u0_back

.LBB0_662:
	s_andn2_saveexec_b64 s[6:7], s[6:7]
	s_cbranch_execz .LBB0_680
	v_mov_b32_e32 v1, s4
	v_add_co_u32_e32 v2, vcc, 0x3000, v1
	v_mov_b32_e32 v1, s5
	s_lshr_b32 s98, 0x160580, s14
	s_and_b32 s98, s98, 1
	v_readlane_b32 s99, v255, 59
	s_and_b32 s98, s98, s99
	s_cmp_eq_u32 s98, 1
	s_cbranch_scc1 .Lwb_skip
	buffer_wbl2 sc1
.Lwb_skip:
	s_waitcnt vmcnt(0)
	v_addc_co_u32_e32 v3, vcc, 0, v1, vcc
	flat_atomic_add v1, v[2:3], v202 offset:1024 sc0
	v_cvt_f32_u32_e32 v2, v0
	v_sub_u32_e32 v3, 0, v0
	s_mov_b64 s[10:11], -1
	v_rcp_iflag_f32_e32 v2, v2
	s_nop 0
	v_mul_f32_e32 v2, 0x4f7ffffe, v2
	v_cvt_u32_f32_e32 v2, v2
	v_mul_lo_u32 v3, v3, v2
	v_mul_hi_u32 v3, v2, v3
	v_add_u32_e32 v2, v2, v3
	s_waitcnt vmcnt(0) lgkmcnt(0)
	v_mul_hi_u32 v2, v1, v2
	v_mul_lo_u32 v3, v2, v0
	v_sub_u32_e32 v3, v1, v3
	v_cmp_ge_u32_e32 vcc, v3, v0
	v_add_u32_e32 v4, 1, v2
	s_nop 0
	v_cndmask_b32_e32 v2, v2, v4, vcc
	v_sub_u32_e32 v4, v3, v0
	v_cndmask_b32_e32 v3, v3, v4, vcc
	v_cmp_ge_u32_e32 vcc, v3, v0
	v_add_u32_e32 v3, 1, v2
	s_nop 0
	v_cndmask_b32_e32 v2, v2, v3, vcc
	v_add_u32_e32 v3, 1, v1
	v_mad_u64_u32 v[0:1], s[6:7], v0, v2, v[0:1]
	s_add_u32 s6, s4, 0x3500
	s_addc_u32 s7, s5, 0
	v_cmp_ne_u32_e32 vcc, v3, v0
	v_mov_b64_e32 v[0:1], s[6:7]
	s_and_saveexec_b64 s[8:9], vcc
	s_cbranch_execz .LBB0_677
	v_mov_b64_e32 v[0:1], s[6:7]
	flat_load_dword v0, v[0:1] sc1
	s_mov_b64 s[42:43], 0
	s_waitcnt vmcnt(0) lgkmcnt(0)
	v_cmp_eq_u32_e32 vcc, v0, v2
	s_and_saveexec_b64 s[40:41], vcc
	s_cbranch_execz .LBB0_676
	s_add_u32 s10, s4, 0x200
	s_addc_u32 s11, s5, 0
	s_mov_b32 s54, 1
	s_mov_b64 s[4:5], 0
	s_branch .LBB0_667
